# P3 loop: shorter back edge (no flag/branch pair), pads replaced by independent cvts, mask row counter derived inside the rare mask block
# baseline (speedup 1.0000x reference)
.LBB0_325:
	s_waitcnt lgkmcnt(0)
	v_mfma_f32_32x32x16_bf16 v[96:111], v[80:83], v[144:147], v[64:79]
	s_add_i32 s0, s74, s97
	s_sub_i32 s0, s0, 63
	v_mfma_f32_32x32x16_bf16 v[96:111], v[202:205], v[140:143], v[96:111]
	v_cvt_f32_i32_e32 v156, s0
	v_mfma_f32_32x32x16_bf16 v[96:111], v[194:197], v[136:139], v[96:111]
	v_fma_f32 v254, v208, v156, -v207
	v_mfma_f32_32x32x16_bf16 v[96:111], v[186:189], v[132:135], v[96:111]
	v_add_f32_e32 v255, v237, v254
	s_add_i32 s3, s79, 0xfffe8000
	s_and_b32 s3, s3, 0x18000
	v_add_u32_e32 v158, s3, v235
	v_add_u32_e32 v159, s3, v239
	v_add_u32_e32 v160, s3, v236
	v_add_u32_e32 v161, s3, v234
	ds_read_b64_tr_b16 v[182:183], v158 offset:32768
	ds_read_b64_tr_b16 v[184:185], v158 offset:34816
	ds_read_b64_tr_b16 v[178:179], v159 offset:32768
	ds_read_b64_tr_b16 v[180:181], v159 offset:34816
	v_mfma_f32_32x32x16_bf16 v[80:95], v[198:201], v[144:147], v[64:79]
	v_add_f32_e32 v96, v254, v96
	v_exp_f32_e32 v96, v96
	v_add_f32_e32 v97, v254, v97
	v_exp_f32_e32 v97, v97
	v_add_f32_e32 v98, v254, v98
	v_exp_f32_e32 v98, v98
	v_add_f32_e32 v99, v254, v99
	v_exp_f32_e32 v99, v99
	v_mfma_f32_32x32x16_bf16 v[80:95], v[190:193], v[140:143], v[80:95]
	v_add_f32_e32 v100, v254, v100
	v_exp_f32_e32 v100, v100
	v_add_f32_e32 v101, v254, v101
	v_exp_f32_e32 v101, v101
	v_add_f32_e32 v102, v254, v102
	v_exp_f32_e32 v102, v102
	v_add_f32_e32 v103, v254, v103
	v_exp_f32_e32 v103, v103
	v_mfma_f32_32x32x16_bf16 v[80:95], v[246:249], v[136:139], v[80:95]
	v_add_f32_e32 v104, v254, v104
	v_exp_f32_e32 v104, v104
	v_add_f32_e32 v105, v254, v105
	v_exp_f32_e32 v105, v105
	v_add_f32_e32 v106, v254, v106
	v_exp_f32_e32 v106, v106
	v_add_f32_e32 v107, v254, v107
	v_exp_f32_e32 v107, v107
	v_mfma_f32_32x32x16_bf16 v[80:95], v[250:253], v[132:135], v[80:95]
	v_add_f32_e32 v108, v254, v108
	v_exp_f32_e32 v108, v108
	v_add_f32_e32 v109, v254, v109
	v_exp_f32_e32 v109, v109
	v_add_f32_e32 v110, v254, v110
	v_exp_f32_e32 v110, v110
	v_add_f32_e32 v111, v254, v111
	v_exp_f32_e32 v111, v111
	s_cmp_le_i32 s97, s78
	s_cbranch_scc1 .LBB0_327
	s_lshl_b32 s4, s72, 6
	v_subrev_u32_e32 v156, s4, v240
	v_cmp_gt_i32_e64 s[60:61], 26, v156
	v_cmp_gt_i32_e64 s[62:63], 27, v156
	v_cmp_gt_i32_e64 s[58:59], 25, v156
	s_and_b64 s[60:61], s[62:63], s[60:61]
	v_cmp_gt_i32_e64 s[56:57], 24, v156
	s_and_b64 s[58:59], s[60:61], s[58:59]
	v_cmp_gt_i32_e64 s[54:55], 19, v156
	s_and_b64 s[56:57], s[58:59], s[56:57]
	v_cmp_gt_i32_e64 s[52:53], 18, v156
	s_and_b64 s[54:55], s[56:57], s[54:55]
	v_cmp_gt_i32_e64 s[50:51], 17, v156
	s_and_b64 s[52:53], s[54:55], s[52:53]
	v_cmp_gt_i32_e64 s[48:49], 16, v156
	s_and_b64 s[50:51], s[52:53], s[50:51]
	v_cmp_gt_i32_e64 s[46:47], 11, v156
	s_and_b64 s[48:49], s[50:51], s[48:49]
	v_cmp_gt_i32_e64 s[44:45], 10, v156
	s_and_b64 s[46:47], s[48:49], s[46:47]
	v_cmp_gt_i32_e64 s[42:43], 9, v156
	s_and_b64 s[44:45], s[46:47], s[44:45]
	v_cmp_gt_i32_e64 s[40:41], 8, v156
	s_and_b64 s[42:43], s[44:45], s[42:43]
	v_cmp_gt_i32_e64 s[38:39], 3, v156
	s_and_b64 s[40:41], s[42:43], s[40:41]
	v_cmp_gt_i32_e64 s[36:37], 2, v156
	s_and_b64 s[38:39], s[40:41], s[38:39]
	v_cmp_gt_i32_e64 s[34:35], 1, v156
	s_and_b64 s[36:37], s[38:39], s[36:37]
	v_cmp_gt_i32_e64 s[30:31], 0, v156
	s_and_b64 s[34:35], s[36:37], s[34:35]
	s_and_b64 s[30:31], s[34:35], s[30:31]
	v_cmp_gt_i32_e64 s[28:29], 58, v156
	v_cndmask_b32_e64 v96, v96, v113, s[30:31]
	v_cmp_gt_i32_e64 s[30:31], 59, v156
	v_cmp_gt_i32_e64 s[26:27], 57, v156
	s_and_b64 s[28:29], s[30:31], s[28:29]
	v_cmp_gt_i32_e64 s[24:25], 56, v156
	s_and_b64 s[26:27], s[28:29], s[26:27]
	v_cmp_gt_i32_e64 s[22:23], 51, v156
	s_and_b64 s[24:25], s[26:27], s[24:25]
	v_cmp_gt_i32_e64 s[20:21], 50, v156
	s_and_b64 s[22:23], s[24:25], s[22:23]
	v_cmp_gt_i32_e64 s[18:19], 49, v156
	s_and_b64 s[20:21], s[22:23], s[20:21]
	v_cmp_gt_i32_e64 s[16:17], 48, v156
	s_and_b64 s[18:19], s[20:21], s[18:19]
	v_cmp_gt_i32_e64 s[14:15], 43, v156
	s_and_b64 s[16:17], s[18:19], s[16:17]
	v_cmp_gt_i32_e64 s[12:13], 42, v156
	s_and_b64 s[14:15], s[16:17], s[14:15]
	v_cmp_gt_i32_e64 s[10:11], 41, v156
	s_and_b64 s[12:13], s[14:15], s[12:13]
	v_cmp_gt_i32_e64 s[8:9], 40, v156
	s_and_b64 s[10:11], s[12:13], s[10:11]
	v_cmp_gt_i32_e64 s[6:7], 35, v156
	s_and_b64 s[8:9], s[10:11], s[8:9]
	v_cmp_gt_i32_e64 s[4:5], 34, v156
	s_and_b64 s[6:7], s[8:9], s[6:7]
	v_cmp_gt_i32_e64 s[0:1], 33, v156
	s_and_b64 s[4:5], s[6:7], s[4:5]
	v_cmp_gt_i32_e32 vcc, 32, v156
	s_and_b64 s[0:1], s[4:5], s[0:1]
	s_and_b64 vcc, s[0:1], vcc
	v_cndmask_b32_e64 v111, v111, v113, s[62:63]
	v_cndmask_b32_e64 v110, v110, v113, s[60:61]
	v_cndmask_b32_e64 v109, v109, v113, s[58:59]
	v_cndmask_b32_e64 v108, v108, v113, s[56:57]
	v_cndmask_b32_e64 v107, v107, v113, s[54:55]
	v_cndmask_b32_e64 v106, v106, v113, s[52:53]
	v_cndmask_b32_e64 v105, v105, v113, s[50:51]
	v_cndmask_b32_e64 v104, v104, v113, s[48:49]
	v_cndmask_b32_e64 v103, v103, v113, s[46:47]
	v_cndmask_b32_e64 v102, v102, v113, s[44:45]
	v_cndmask_b32_e64 v101, v101, v113, s[42:43]
	v_cndmask_b32_e64 v100, v100, v113, s[40:41]
	v_cndmask_b32_e64 v99, v99, v113, s[38:39]
	v_cndmask_b32_e64 v98, v98, v113, s[36:37]
	v_cndmask_b32_e64 v97, v97, v113, s[34:35]
	v_cndmask_b32_e64 v95, v95, v228, s[30:31]
	v_cndmask_b32_e64 v94, v94, v228, s[28:29]
	v_cndmask_b32_e64 v93, v93, v228, s[26:27]
	v_cndmask_b32_e64 v92, v92, v228, s[24:25]
	v_cndmask_b32_e64 v91, v91, v228, s[22:23]
	v_cndmask_b32_e64 v90, v90, v228, s[20:21]
	v_cndmask_b32_e64 v89, v89, v228, s[18:19]
	v_cndmask_b32_e64 v88, v88, v228, s[16:17]
	v_cndmask_b32_e64 v87, v87, v228, s[14:15]
	v_cndmask_b32_e64 v86, v86, v228, s[12:13]
	v_cndmask_b32_e64 v85, v85, v228, s[10:11]
	v_cndmask_b32_e64 v84, v84, v228, s[8:9]
	v_cndmask_b32_e64 v83, v83, v228, s[6:7]
	v_cndmask_b32_e64 v82, v82, v228, s[4:5]
	v_cndmask_b32_e64 v81, v81, v228, s[0:1]
	v_cndmask_b32_e32 v80, v80, v228, vcc
.LBB0_327:
	s_waitcnt lgkmcnt(2)
	v_mfma_f32_32x32x16_bf16 v[48:63], v[182:185], v[174:177], v[48:63]
	v_add_f32_e32 v190, v255, v80
	v_exp_f32_e32 v190, v190
	ds_read_b64_tr_b16 v[148:149], v160 offset:32768
	ds_read_b64_tr_b16 v[150:151], v160 offset:34816
	v_add_f32_e32 v157, v190, v96
	s_waitcnt lgkmcnt(2)
	v_mfma_f32_32x32x16_bf16 v[32:47], v[178:181], v[174:177], v[32:47]
	v_add_f32_e32 v191, v255, v81
	v_exp_f32_e32 v191, v191
	ds_read_b64_tr_b16 v[152:153], v161 offset:32768
	ds_read_b64_tr_b16 v[154:155], v161 offset:34816
	v_add_f32_e32 v156, v191, v97
	v_add_f32_e32 v157, v156, v157
	s_waitcnt lgkmcnt(2)
	v_mfma_f32_32x32x16_bf16 v[16:31], v[148:151], v[174:177], v[16:31]
	v_add_f32_e32 v192, v255, v82
	v_exp_f32_e32 v192, v192
	ds_read_b64_tr_b16 v[182:183], v158 offset:36864
	ds_read_b64_tr_b16 v[184:185], v158 offset:38912
	v_add_f32_e32 v156, v192, v98
	v_add_f32_e32 v157, v156, v157
	s_waitcnt lgkmcnt(2)
	v_mfma_f32_32x32x16_bf16 v[0:15], v[152:155], v[174:177], v[0:15]
	v_add_f32_e32 v193, v255, v83
	v_exp_f32_e32 v193, v193
	ds_read_b64_tr_b16 v[178:179], v159 offset:36864
	ds_read_b64_tr_b16 v[180:181], v159 offset:38912
	v_add_f32_e32 v156, v193, v99
	v_add_f32_e32 v157, v156, v157
	v_cvt_pk_bf16_f32 v174, v96, v97
	s_waitcnt lgkmcnt(2)
	v_mfma_f32_32x32x16_bf16 v[48:63], v[182:185], v[162:165], v[48:63]
	v_add_f32_e32 v194, v255, v84
	v_exp_f32_e32 v194, v194
	ds_read_b64_tr_b16 v[148:149], v160 offset:36864
	ds_read_b64_tr_b16 v[150:151], v160 offset:38912
	v_add_f32_e32 v156, v194, v100
	v_add_f32_e32 v157, v156, v157
	v_cvt_pk_bf16_f32 v175, v98, v99
	s_waitcnt lgkmcnt(2)
	v_mfma_f32_32x32x16_bf16 v[32:47], v[178:181], v[162:165], v[32:47]
	v_add_f32_e32 v195, v255, v85
	v_exp_f32_e32 v195, v195
	ds_read_b64_tr_b16 v[152:153], v161 offset:36864
	ds_read_b64_tr_b16 v[154:155], v161 offset:38912
	v_add_f32_e32 v156, v195, v101
	v_add_f32_e32 v157, v156, v157
	v_cvt_pk_bf16_f32 v176, v100, v101
	s_waitcnt lgkmcnt(2)
	v_mfma_f32_32x32x16_bf16 v[16:31], v[148:151], v[162:165], v[16:31]
	v_add_f32_e32 v196, v255, v86
	v_exp_f32_e32 v196, v196
	ds_read_b64_tr_b16 v[182:183], v158 offset:40960
	ds_read_b64_tr_b16 v[184:185], v158 offset:43008
	v_add_f32_e32 v156, v196, v102
	v_add_f32_e32 v157, v156, v157
	v_cvt_pk_bf16_f32 v177, v102, v103
	s_waitcnt lgkmcnt(2)
	v_mfma_f32_32x32x16_bf16 v[0:15], v[152:155], v[162:165], v[0:15]
	v_add_f32_e32 v197, v255, v87
	v_exp_f32_e32 v197, v197
	ds_read_b64_tr_b16 v[178:179], v159 offset:40960
	ds_read_b64_tr_b16 v[180:181], v159 offset:43008
	v_add_f32_e32 v156, v197, v103
	v_add_f32_e32 v157, v156, v157
	v_cvt_pk_bf16_f32 v162, v104, v105
	s_waitcnt lgkmcnt(2)
	v_mfma_f32_32x32x16_bf16 v[48:63], v[182:185], v[170:173], v[48:63]
	v_add_f32_e32 v198, v255, v88
	v_exp_f32_e32 v198, v198
	ds_read_b64_tr_b16 v[148:149], v160 offset:40960
	ds_read_b64_tr_b16 v[150:151], v160 offset:43008
	v_add_f32_e32 v156, v198, v104
	v_add_f32_e32 v157, v156, v157
	v_cvt_pk_bf16_f32 v163, v106, v107
	s_waitcnt lgkmcnt(2)
	v_mfma_f32_32x32x16_bf16 v[32:47], v[178:181], v[170:173], v[32:47]
	v_add_f32_e32 v199, v255, v89
	v_exp_f32_e32 v199, v199
	ds_read_b64_tr_b16 v[152:153], v161 offset:40960
	ds_read_b64_tr_b16 v[154:155], v161 offset:43008
	v_add_f32_e32 v156, v199, v105
	v_add_f32_e32 v157, v156, v157
	v_cvt_pk_bf16_f32 v164, v108, v109
	s_waitcnt lgkmcnt(2)
	v_mfma_f32_32x32x16_bf16 v[16:31], v[148:151], v[170:173], v[16:31]
	v_add_f32_e32 v200, v255, v90
	v_exp_f32_e32 v200, v200
	ds_read_b64_tr_b16 v[182:183], v158 offset:45056
	ds_read_b64_tr_b16 v[184:185], v158 offset:47104
	v_add_f32_e32 v156, v200, v106
	v_add_f32_e32 v157, v156, v157
	v_cvt_pk_bf16_f32 v165, v110, v111
	s_waitcnt lgkmcnt(2)
	v_mfma_f32_32x32x16_bf16 v[0:15], v[152:155], v[170:173], v[0:15]
	v_add_f32_e32 v201, v255, v91
	v_exp_f32_e32 v201, v201
	ds_read_b64_tr_b16 v[178:179], v159 offset:45056
	ds_read_b64_tr_b16 v[180:181], v159 offset:47104
	v_add_f32_e32 v156, v201, v107
	v_add_f32_e32 v157, v156, v157
	v_cvt_pk_bf16_f32 v170, v190, v191
	s_waitcnt lgkmcnt(2)
	v_mfma_f32_32x32x16_bf16 v[48:63], v[182:185], v[166:169], v[48:63]
	v_add_f32_e32 v202, v255, v92
	v_exp_f32_e32 v202, v202
	ds_read_b64_tr_b16 v[148:149], v160 offset:45056
	ds_read_b64_tr_b16 v[150:151], v160 offset:47104
	v_add_f32_e32 v156, v202, v108
	v_add_f32_e32 v157, v156, v157
	v_cvt_pk_bf16_f32 v171, v192, v193
	s_waitcnt lgkmcnt(2)
	v_mfma_f32_32x32x16_bf16 v[32:47], v[178:181], v[166:169], v[32:47]
	v_add_f32_e32 v203, v255, v93
	v_exp_f32_e32 v203, v203
	ds_read_b64_tr_b16 v[152:153], v161 offset:45056
	ds_read_b64_tr_b16 v[154:155], v161 offset:47104
	v_add_f32_e32 v156, v203, v109
	v_add_f32_e32 v157, v156, v157
	v_cvt_pk_bf16_f32 v172, v194, v195
	s_waitcnt lgkmcnt(2)
	v_mfma_f32_32x32x16_bf16 v[16:31], v[148:151], v[166:169], v[16:31]
	v_add_f32_e32 v204, v255, v94
	v_exp_f32_e32 v204, v204
	v_cvt_pk_bf16_f32 v173, v196, v197
	v_add_f32_e32 v156, v204, v110
	v_add_f32_e32 v157, v156, v157
	s_waitcnt lgkmcnt(0)
	v_mfma_f32_32x32x16_bf16 v[0:15], v[152:155], v[166:169], v[0:15]
	v_add_f32_e32 v205, v255, v95
	v_exp_f32_e32 v205, v205
	v_cvt_pk_bf16_f32 v166, v198, v199
	v_add_f32_e32 v156, v205, v111
	v_add_f32_e32 v157, v156, v157
	v_cvt_pk_bf16_f32 v167, v200, v201
	v_cvt_pk_bf16_f32 v168, v202, v203
	v_cvt_pk_bf16_f32 v169, v204, v205
	s_add_i32 s72, s72, 1
	s_add_i32 s79, s79, 0x8000
	s_add_i32 s97, s97, 64
	s_add_i32 s1, s72, 1
	v_add_f32_e32 v229, v229, v157
	s_cmp_ge_i32 s1, s82
	s_cbranch_scc1 .LBB0_332
	s_cmp_ge_i32 s72, s73
	s_cbranch_scc1 .Lk_last
	s_waitcnt vmcnt(4) lgkmcnt(0)
	s_barrier
	s_branch .LBB0_323
.Lk_last:
	s_waitcnt vmcnt(0) lgkmcnt(0)
	s_barrier
	s_branch .LBB0_323
